# gMLP early loads + chunk workgroups take rows [0,3072) of the row passes
# baseline (speedup 1.0000x reference)
; __global__ void __launch_bounds__(512, 2) mega_fwd(Args a_) {
;     ...
;             case 2: if constexpr (PH_ON(2)) {
;                 for (int u = ti.bid; u < Mr / 128; u += ti.nblk) gmlp_unit(ti, a, l, u, lds);
;                 qk_rows(a, l, gw, ngw, lane);
;                 lora_in_rows(a, l, gw, ngw, lane);
.LBB0_449:
	s_movk_i32 s99, 0x4800
	s_sub_i32 s3, s0, s10
	s_cmp_lt_i32 s3, 64
	s_cbranch_scc1 .Lrows_default
	s_cmp_lt_i32 s2, s10
	s_cbranch_scc1 .Lrows_none
	s_sub_i32 s2, s2, s10
	s_mov_b32 s0, s3
	v_readlane_b32 s3, v255, 42
	s_lshl_b32 s48, s2, 3
	s_lshl_b32 s80, s0, 3
	s_nop 1
	s_add_i32 s48, s48, s3
	s_addk_i32 s48, 0xc00
	s_branch .Lrows_default
.Lrows_none:
	s_mov_b32 s0, s10
	v_readlane_b32 s3, v255, 42
	s_lshl_b32 s48, s2, 3
	s_lshl_b32 s80, s0, 3
	s_nop 1
	s_add_i32 s48, s48, s3
	s_movk_i32 s99, 0xc00
